# attention unit prologue: all Q/K/V/Kr loads issued at once (one wait); epilogue: O tile transposed via per-wave LDS scratch, stored as whole 128B rows
# baseline (speedup 1.0000x reference)
.LBB0_730:
	v_and_b32_e32 v33, 64, v187
	v_xor_b32_e32 v32, 32, v187
	v_add_u32_e32 v33, 64, v33
	v_cmp_lt_i32_e32 vcc, v32, v33
	v_mov_b32_e32 v161, v97
	s_add_i32 s36, s36, s72
	v_cndmask_b32_e32 v32, v187, v32, vcc
	v_lshlrev_b32_e32 v32, 2, v32
	ds_bpermute_b32 v32, v32, v157
	s_cmpk_lt_i32 s36, 0x400
	s_waitcnt lgkmcnt(0)
	v_add_f32_e32 v32, v157, v32
	v_div_scale_f32 v33, s[0:1], v32, v32, 1.0
	v_rcp_f32_e32 v34, v33
	v_div_scale_f32 v35, vcc, 1.0, v32, 1.0
	v_fma_f32 v36, -v33, v34, 1.0
	v_fmac_f32_e32 v34, v36, v34
	v_mul_f32_e32 v36, v35, v34
	v_fma_f32 v37, -v33, v36, v35
	v_fmac_f32_e32 v36, v37, v34
	v_fma_f32 v33, -v33, v36, v35
	v_div_fmas_f32 v33, v33, v34, v36
	v_div_fixup_f32 v32, v33, v32, 1.0
	v_mul_u32_u24_e32 v36, 0x90, v137
	v_add_u32_e32 v36, v36, v160
	v_add_u32_e32 v36, 0x10200, v36
	v_and_b32_e32 v38, 31, v187
	v_lshrrev_b32_e32 v39, 3, v187
	v_sub_u32_e32 v40, v39, v38
	v_add_u32_e32 v37, v137, v40
	v_mul_u32_u24_e32 v37, 0x90, v37
	v_and_b32_e32 v41, 7, v187
	v_lshlrev_b32_e32 v41, 4, v41
	v_add_u32_e32 v37, v37, v41
	v_add_u32_e32 v37, 0x10200, v37
	v_lshl_add_u32 v38, v40, 10, v41
	v_ashrrev_i32_e32 v39, 31, v38
	v_lshl_add_u64 v[34:35], v[166:167], 0, v[38:39]
	v_pk_mul_f32 v[0:1], v[0:1], v[32:33] op_sel_hi:[1,0]
	v_pk_mul_f32 v[2:3], v[2:3], v[32:33] op_sel_hi:[1,0]
	v_cvt_pk_bf16_f32 v0, v0, v1
	v_cvt_pk_bf16_f32 v1, v2, v3
	ds_write_b64 v36, v[0:1]
	v_pk_mul_f32 v[4:5], v[4:5], v[32:33] op_sel_hi:[1,0]
	v_pk_mul_f32 v[6:7], v[6:7], v[32:33] op_sel_hi:[1,0]
	v_cvt_pk_bf16_f32 v4, v4, v5
	v_cvt_pk_bf16_f32 v5, v6, v7
	ds_write_b64 v36, v[4:5] offset:16
	v_pk_mul_f32 v[8:9], v[8:9], v[32:33] op_sel_hi:[1,0]
	v_pk_mul_f32 v[10:11], v[10:11], v[32:33] op_sel_hi:[1,0]
	v_cvt_pk_bf16_f32 v8, v8, v9
	v_cvt_pk_bf16_f32 v9, v10, v11
	ds_write_b64 v36, v[8:9] offset:32
	v_pk_mul_f32 v[12:13], v[12:13], v[32:33] op_sel_hi:[1,0]
	v_pk_mul_f32 v[14:15], v[14:15], v[32:33] op_sel_hi:[1,0]
	v_cvt_pk_bf16_f32 v12, v12, v13
	v_cvt_pk_bf16_f32 v13, v14, v15
	ds_write_b64 v36, v[12:13] offset:48
	v_pk_mul_f32 v[16:17], v[16:17], v[32:33] op_sel_hi:[1,0]
	v_pk_mul_f32 v[18:19], v[18:19], v[32:33] op_sel_hi:[1,0]
	v_cvt_pk_bf16_f32 v16, v16, v17
	v_cvt_pk_bf16_f32 v17, v18, v19
	ds_write_b64 v36, v[16:17] offset:64
	v_pk_mul_f32 v[20:21], v[20:21], v[32:33] op_sel_hi:[1,0]
	v_pk_mul_f32 v[22:23], v[22:23], v[32:33] op_sel_hi:[1,0]
	v_cvt_pk_bf16_f32 v20, v20, v21
	v_cvt_pk_bf16_f32 v21, v22, v23
	ds_write_b64 v36, v[20:21] offset:80
	v_pk_mul_f32 v[24:25], v[24:25], v[32:33] op_sel_hi:[1,0]
	v_pk_mul_f32 v[26:27], v[26:27], v[32:33] op_sel_hi:[1,0]
	v_cvt_pk_bf16_f32 v24, v24, v25
	v_cvt_pk_bf16_f32 v25, v26, v27
	ds_write_b64 v36, v[24:25] offset:96
	v_pk_mul_f32 v[28:29], v[28:29], v[32:33] op_sel_hi:[1,0]
	v_pk_mul_f32 v[30:31], v[30:31], v[32:33] op_sel_hi:[1,0]
	v_cvt_pk_bf16_f32 v28, v28, v29
	v_cvt_pk_bf16_f32 v29, v30, v31
	ds_write_b64 v36, v[28:29] offset:112
	s_waitcnt lgkmcnt(0)
	ds_read_b128 v[0:3], v37
	ds_read_b128 v[4:7], v37 offset:1152
	ds_read_b128 v[8:11], v37 offset:2304
	ds_read_b128 v[12:15], v37 offset:3456
	s_mov_b64 s[8:9], 0x2000
	s_waitcnt lgkmcnt(3)
	global_store_dwordx4 v[34:35], v[0:3], off
	v_lshl_add_u64 v[34:35], v[34:35], 0, s[8:9]
	s_waitcnt lgkmcnt(2)
	global_store_dwordx4 v[34:35], v[4:7], off
	v_lshl_add_u64 v[34:35], v[34:35], 0, s[8:9]
	s_waitcnt lgkmcnt(1)
	global_store_dwordx4 v[34:35], v[8:11], off
	v_lshl_add_u64 v[34:35], v[34:35], 0, s[8:9]
	s_waitcnt lgkmcnt(0)
	global_store_dwordx4 v[34:35], v[12:15], off
	s_cbranch_scc0 .LBB0_762
.LBB0_731:
	s_ashr_i32 s0, s36, 4
	s_ashr_i32 s6, s36, 7
	s_and_b32 s10, s0, 7
	s_mul_hi_i32 s1, s0, 0x88000
	s_mul_i32 s0, s0, 0x88000
	s_add_u32 s4, s37, s0
	s_addc_u32 s5, s38, s1
	s_ashr_i32 s7, s6, 31
	s_lshl_b64 s[8:9], s[6:7], 12
	s_lshl_b32 s7, s36, 8
	s_and_b32 s7, s7, 0xf00
	v_add_u32_e32 v96, s7, v137
	v_lshl_add_u64 v[0:1], s[8:9], 0, v[96:97]
	v_lshlrev_b64 v[2:3], 10, v[0:1]
	v_lshlrev_b64 v[0:1], 9, v[0:1]
	s_lshl_b32 s24, s10, 6
	v_lshl_add_u64 v[0:1], s[54:55], 0, v[0:1]
	v_lshl_add_u64 v[0:1], v[0:1], 0, s[24:25]
	v_lshl_add_u64 v[2:3], s[22:23], 0, v[2:3]
	s_lshl_b32 s8, s10, 7
	s_mov_b32 s9, s25
	v_lshl_add_u64 v[0:1], v[0:1], 0, v[162:163]
	v_lshl_add_u64 v[166:167], v[2:3], 0, s[8:9]
	v_add_co_u32_e32 v0, vcc, 0x4400000, v0
	v_lshl_add_u64 v[2:3], v[166:167], 0, v[162:163]
	s_nop 0
	v_addc_co_u32_e32 v1, vcc, 0, v1, vcc
	global_load_dwordx4 v[100:103], v[2:3], off
	global_load_dwordx4 v[104:107], v[2:3], off offset:32
	global_load_dwordx4 v[108:111], v[2:3], off offset:64
	global_load_dwordx4 v[112:115], v[2:3], off offset:96
	global_load_dwordx4 v[116:119], v[0:1], off
	global_load_dwordx4 v[120:123], v[0:1], off offset:32
	s_mul_i32 s34, s6, 0x44000
	s_mul_hi_i32 s35, s6, 0x44000
	s_add_u32 s6, s39, s34
	s_addc_u32 s7, s40, s35
	global_load_dwordx4 v[188:191], v154, s[4:5]
	s_add_u32 s12, s4, 0x2000
	s_addc_u32 s13, s5, 0
	global_load_dwordx4 v[128:131], v154, s[12:13]
	v_and_b32_e32 v196, 0xfff, v152
	global_load_dwordx4 v[124:127], v196, s[6:7]
	s_add_u32 s12, s6, 0x1000
	s_addc_u32 s13, s7, 0
	global_load_dwordx4 v[192:195], v196, s[12:13]
	v_lshl_add_u64 v[12:13], v[150:151], 0, s[0:1]
	global_load_dwordx4 v[4:7], v[12:13], off
	global_load_dwordx4 v[132:135], v[12:13], off offset:128
	v_add_u32_e32 v9, v143, v148
	v_add3_u32 v0, v177, v148, s41
	v_add_u32_e32 v1, v178, v148
	v_mov_b32_e32 v159, v97
	s_waitcnt vmcnt(0)
	ds_write_b128 v9, v[188:191]
	ds_write_b128 v186, v[124:127] offset:128
	ds_write2_b64 v0, v[4:5], v[6:7] offset1:1
	ds_write_b128 v1, v[128:131] offset:22016
	ds_write_b128 v186, v[192:195] offset:22144
	ds_write2_b64 v149, v[132:133], v[134:135] offset1:1
	s_waitcnt lgkmcnt(0)
	s_barrier
	ds_read_b128 v[0:3], v185
	ds_read_b128 v[4:7], v185 offset:32
	s_waitcnt lgkmcnt(1)
	v_mfma_f32_32x32x16_bf16 v[48:63], v[0:3], v[100:103], 0
	s_mov_b32 s4, 0
	s_mov_b32 s5, s4
	s_mov_b32 s6, s4
	s_mov_b32 s7, s4
	s_mov_b32 s8, s4
	s_mov_b32 s9, s4
	s_mov_b32 s10, s4
	s_waitcnt lgkmcnt(0)
	v_mfma_f32_32x32x16_bf16 v[48:63], v[4:7], v[104:107], v[48:63]
	ds_read_b128 v[0:3], v185 offset:64
	ds_read_b128 v[4:7], v185 offset:96
	s_mov_b32 s11, s4
	s_mov_b32 s12, s4
	s_mov_b32 s13, s4
	s_mov_b32 s14, s4
	s_mov_b32 s15, s4
	s_mov_b32 s16, s4
	s_waitcnt lgkmcnt(1)
	v_mfma_f32_32x32x16_bf16 v[48:63], v[0:3], v[108:111], v[48:63]
	s_mov_b32 s17, s4
	s_mov_b32 s18, s4
	s_mov_b32 s19, s4
	s_waitcnt lgkmcnt(0)
	v_mfma_f32_32x32x16_bf16 v[48:63], v[4:7], v[112:115], v[48:63]
	ds_read_b128 v[0:3], v185 offset:128
	ds_read_b128 v[4:7], v185 offset:160
	s_waitcnt lgkmcnt(1)
	v_mfma_f32_32x32x16_bf16 v[48:63], v[0:3], v[116:119], v[48:63]
	s_waitcnt lgkmcnt(0)
	v_mfma_f32_32x32x16_bf16 v[48:63], v[4:7], v[120:123], v[48:63]
	ds_read_b128 v[0:3], v185 offset:6656
	ds_read_b128 v[4:7], v185 offset:6688
	s_waitcnt lgkmcnt(1)
	v_mfma_f32_32x32x16_bf16 v[32:47], v[0:3], v[100:103], 0
	s_waitcnt lgkmcnt(0)
	v_mfma_f32_32x32x16_bf16 v[32:47], v[4:7], v[104:107], v[32:47]
	ds_read_b128 v[0:3], v185 offset:6720
	ds_read_b128 v[4:7], v185 offset:6752
	ds_read_b128 v[16:19], v185 offset:6816
	s_waitcnt lgkmcnt(2)
	v_mfma_f32_32x32x16_bf16 v[32:47], v[0:3], v[108:111], v[32:47]
	ds_read_b128 v[0:3], v185 offset:6784
	s_waitcnt lgkmcnt(2)
	v_mfma_f32_32x32x16_bf16 v[32:47], v[4:7], v[112:115], v[32:47]
	s_waitcnt lgkmcnt(0)
	v_mfma_f32_32x32x16_bf16 v[32:47], v[0:3], v[116:119], v[32:47]
	v_mov_b64_e32 v[0:1], s[4:5]
	v_mov_b64_e32 v[2:3], s[6:7]
	v_mov_b64_e32 v[4:5], s[8:9]
	v_mov_b64_e32 v[6:7], s[10:11]
	v_mov_b64_e32 v[8:9], s[12:13]
	v_mov_b64_e32 v[10:11], s[14:15]
	v_mov_b64_e32 v[12:13], s[16:17]
	v_mfma_f32_32x32x16_bf16 v[32:47], v[16:19], v[120:123], v[32:47]
	v_mov_b64_e32 v[14:15], s[18:19]
	s_nop 15
	s_nop 15
	s_nop 15
	v_mov_b64_e32 v[30:31], v[14:15]
	v_lshl_add_u64 v[98:99], v[152:153], 0, s[34:35]
	v_lshl_add_u64 v[168:169], v[146:147], 0, s[0:1]
	v_lshl_add_u64 v[170:171], v[154:155], 0, s[0:1]
	v_mov_b32_e32 v157, 0
	v_mov_b64_e32 v[28:29], v[12:13]
	v_mov_b64_e32 v[26:27], v[10:11]
	v_mov_b64_e32 v[24:25], v[8:9]
	v_mov_b64_e32 v[22:23], v[6:7]
	v_mov_b64_e32 v[20:21], v[4:5]
	v_mov_b64_e32 v[18:19], v[2:3]
	v_mov_b64_e32 v[16:17], v[0:1]
	v_mov_b32_e32 v96, 0
	v_mov_b32_e32 v228, 0x80000000
	v_mov_b32_e32 v229, v228
	v_mov_b32_e32 v230, v228
	v_mov_b32_e32 v231, v228
	v_mov_b32_e32 v232, v228
	v_mov_b32_e32 v233, v228
	v_mov_b32_e32 v234, v228
	v_mov_b32_e32 v235, v228
	v_mov_b32_e32 v236, v228
	v_mov_b32_e32 v237, v228
	v_mov_b32_e32 v238, v228
	v_mov_b32_e32 v239, v228
	v_mov_b32_e32 v240, v228
	v_mov_b32_e32 v241, v228
	v_mov_b32_e32 v242, v228
	v_mov_b32_e32 v243, v228
	s_add_u32 s48, s37, s0
	s_addc_u32 s49, s38, s1
	s_add_u32 s48, s48, 0x4000
	s_addc_u32 s49, s49, 0
	s_add_u32 s50, s39, s34
	s_addc_u32 s51, s40, s35
	s_add_u32 s50, s50, 0x2000
	s_addc_u32 s51, s51, 0
	s_add_u32 s60, s54, 0x1cd00000
	s_addc_u32 s61, s55, 0
	s_add_u32 s60, s60, s0
	s_addc_u32 s61, s61, s1
	s_add_u32 s60, s60, 0x100
	s_addc_u32 s61, s61, 0
	s_mov_b32 s44, 0
	s_movk_i32 s45, 0x5600
	s_mov_b32 s46, 0xac00
	v_add_u32_e32 v168, v141, v148
	v_add_u32_e32 v169, v174, v175
	v_add3_u32 v170, v176, v148, s41
	v_add3_u32 v171, v182, v136, s41
	v_add3_u32 v172, v183, v136, s41
	v_add_u32_e32 v173, v180, v179
	v_add_u32_e32 v98, v181, v179
	v_and_b32_e32 v99, 0xfff, v152
	v_mov_b32_e32 v212, 0
	v_mov_b32_e32 v213, 0
	v_mov_b32_e32 v214, 0
	v_mov_b32_e32 v215, 0
	v_mov_b32_e32 v216, 0
	v_mov_b32_e32 v217, 0
	v_mov_b32_e32 v218, 0
	v_mov_b32_e32 v219, 0
	v_mov_b32_e32 v220, 0
	v_mov_b32_e32 v221, 0
	v_mov_b32_e32 v222, 0
	v_mov_b32_e32 v223, 0
	global_load_dwordx4 v[128:131], v154, s[48:49]
	global_load_dwordx4 v[124:127], v99, s[50:51]
	global_load_dwordx4 v[132:135], v146, s[60:61]
